# wtrans_tile w_in variant (both copies): the sixteen predicated row loads are issued together and written to LDS behind counted waits, instead of load-wait-write sixteen times
# speedup vs baseline: 1.0179x; 1.0040x over previous
; DI void wtrans_tile(const float* __restrict__ src, int K, int N, u16* __restrict__ dst, int ldw, int tk, int tn,
;                     const float* __restrict__ kscale, char* lds) {
;     ...
;   __syncthreads();
; #pragma unroll
;   for (int q = 0; q < 16; ++q) {
;     int i = i0 + 4 * q;
;     float v = (n0 + j < N) ? src[(size_t)(k0 + i) * N + n0 + j] : 0.f;
;     if (kscale) v *= kscale[k0 + i];
;     t[i * 65 + j] = v;
;   }
;   __syncthreads();
.LBB0_131:
	s_andn2_b64 vcc, exec, s[8:9]
	s_cbranch_vccnz .LBB0_14
	s_mul_hi_i32 s8, s12, 0x2e8ba2e9
	s_lshr_b32 s9, s8, 31
	s_ashr_i32 s8, s8, 3
	s_add_i32 s8, s8, s9
	s_mul_i32 s9, s8, 44
	s_sub_i32 s9, s12, s9
	v_mov_b32_e32 v0, v248
	s_lshl_b32 s12, s8, 6
	v_and_b32_e32 v1, 63, v0
	s_lshl_b32 s8, s9, 6
	v_or_b32_e32 v2, s8, v1
	s_movk_i32 s9, 0xab0
	v_cmp_gt_i32_e32 vcc, s9, v2
	s_ashr_i32 s9, s8, 31
	s_lshl_b64 s[14:15], s[8:9], 2
	s_add_u32 s14, s60, s14
	s_addc_u32 s15, s61, s15
	v_lshlrev_b32_e32 v74, 2, v1
	v_ashrrev_i32_e32 v0, 6, v0
	v_lshl_add_u64 v[2:3], s[14:15], 0, v[74:75]
	v_mov_b32_e32 v4, 0
	v_mov_b32_e32 v6, 0
	s_waitcnt lgkmcnt(0)
	s_barrier
	v_mov_b32_e32 v218, 0
	v_mov_b32_e32 v219, 0
	v_mov_b32_e32 v220, 0
	v_mov_b32_e32 v221, 0
	v_mov_b32_e32 v222, 0
	v_mov_b32_e32 v223, 0
	v_mov_b32_e32 v224, 0
	v_mov_b32_e32 v225, 0
	v_mov_b32_e32 v226, 0
	v_mov_b32_e32 v227, 0
	v_mov_b32_e32 v228, 0
	v_mov_b32_e32 v229, 0
	v_mov_b32_e32 v230, 0
	v_mov_b32_e32 v231, 0
	v_mov_b32_e32 v232, 0
	v_mov_b32_e32 v233, 0
	s_and_saveexec_b64 s[14:15], vcc
	s_cbranch_execz .Lwin_skip_a
	v_add_u32_e32 v5, s12, v0
	v_mad_i64_i32 v[6:7], s[28:29], v5, s96, v[2:3]
	s_lshl_b32 s28, s96, 2
	s_mov_b32 s29, 0
	global_load_dword v218, v[6:7], off
	v_lshl_add_u64 v[6:7], v[6:7], 0, s[28:29]
	global_load_dword v219, v[6:7], off
	v_lshl_add_u64 v[6:7], v[6:7], 0, s[28:29]
	global_load_dword v220, v[6:7], off
	v_lshl_add_u64 v[6:7], v[6:7], 0, s[28:29]
	global_load_dword v221, v[6:7], off
	v_lshl_add_u64 v[6:7], v[6:7], 0, s[28:29]
	global_load_dword v222, v[6:7], off
	v_lshl_add_u64 v[6:7], v[6:7], 0, s[28:29]
	global_load_dword v223, v[6:7], off
	v_lshl_add_u64 v[6:7], v[6:7], 0, s[28:29]
	global_load_dword v224, v[6:7], off
	v_lshl_add_u64 v[6:7], v[6:7], 0, s[28:29]
	global_load_dword v225, v[6:7], off
	v_lshl_add_u64 v[6:7], v[6:7], 0, s[28:29]
	global_load_dword v226, v[6:7], off
	v_lshl_add_u64 v[6:7], v[6:7], 0, s[28:29]
	global_load_dword v227, v[6:7], off
	v_lshl_add_u64 v[6:7], v[6:7], 0, s[28:29]
	global_load_dword v228, v[6:7], off
	v_lshl_add_u64 v[6:7], v[6:7], 0, s[28:29]
	global_load_dword v229, v[6:7], off
	v_lshl_add_u64 v[6:7], v[6:7], 0, s[28:29]
	global_load_dword v230, v[6:7], off
	v_lshl_add_u64 v[6:7], v[6:7], 0, s[28:29]
	global_load_dword v231, v[6:7], off
	v_lshl_add_u64 v[6:7], v[6:7], 0, s[28:29]
	global_load_dword v232, v[6:7], off
	v_lshl_add_u64 v[6:7], v[6:7], 0, s[28:29]
	global_load_dword v233, v[6:7], off
.Lwin_skip_a:
	s_or_b64 exec, exec, s[14:15]
	v_mul_lo_u32 v5, v0, s57
	v_add3_u32 v7, s88, v5, v74
	s_waitcnt vmcnt(15)
	ds_write_b32 v7, v218
	s_waitcnt vmcnt(14)
	ds_write_b32 v7, v219 offset:1040
	s_waitcnt vmcnt(13)
	ds_write_b32 v7, v220 offset:2080
	s_waitcnt vmcnt(12)
	ds_write_b32 v7, v221 offset:3120
	s_waitcnt vmcnt(11)
	ds_write_b32 v7, v222 offset:4160
	s_waitcnt vmcnt(10)
	ds_write_b32 v7, v223 offset:5200
	s_waitcnt vmcnt(9)
	ds_write_b32 v7, v224 offset:6240
	s_waitcnt vmcnt(8)
	ds_write_b32 v7, v225 offset:7280
	s_waitcnt vmcnt(7)
	ds_write_b32 v7, v226 offset:8320
	s_waitcnt vmcnt(6)
	ds_write_b32 v7, v227 offset:9360
	s_waitcnt vmcnt(5)
	ds_write_b32 v7, v228 offset:10400
	s_waitcnt vmcnt(4)
	ds_write_b32 v7, v229 offset:11440
	s_waitcnt vmcnt(3)
	ds_write_b32 v7, v230 offset:12480
	s_waitcnt vmcnt(2)
	ds_write_b32 v7, v231 offset:13520
	s_waitcnt vmcnt(1)
	ds_write_b32 v7, v232 offset:14560
	s_waitcnt vmcnt(0)
	ds_write_b32 v7, v233 offset:15600
	s_ashr_i32 s13, s12, 31
	s_lshl_b64 s[12:13], s[12:13], 1
	s_add_u32 s12, s84, s12
	v_mov_b32_e32 v4, s88
	s_addc_u32 s13, s85, s13
	v_lshlrev_b32_e32 v74, 1, v1
	v_mad_u32_u24 v10, v1, s57, v4
	v_add_u32_e32 v4, 8, v0
	v_add_u32_e32 v6, 16, v0
	v_add_u32_e32 v8, 24, v0
	s_mov_b32 s9, 1
	v_lshl_add_u64 v[2:3], s[12:13], 0, v[74:75]
	v_mov_b32_e32 v1, v0
	s_mov_b32 s12, s8
	v_mov_b32_e32 v5, v4
	s_mov_b32 s13, 16
	v_mov_b32_e32 v7, v6
	v_mov_b32_e32 v9, v8
	s_mov_b32 s14, 0
	s_waitcnt lgkmcnt(0)
	s_barrier

; DI void wtrans_tile(const float* __restrict__ src, int K, int N, u16* __restrict__ dst, int ldw, int tk, int tn,
;                     const float* __restrict__ kscale, char* lds) {
;     ...
;   __syncthreads();
; #pragma unroll
;   for (int q = 0; q < 16; ++q) {
;     int i = i0 + 4 * q;
;     float v = (n0 + j < N) ? src[(size_t)(k0 + i) * N + n0 + j] : 0.f;
;     if (kscale) v *= kscale[k0 + i];
;     t[i * 65 + j] = v;
;   }
;   __syncthreads();
.LBB0_501:
	s_andn2_b64 vcc, exec, s[0:1]
	s_cbranch_vccnz .LBB0_536
	s_and_b32 s0, s3, 0xffff
	s_mul_i32 s0, s0, 0xba2f
	s_lshr_b32 s1, s0, 21
	s_mul_i32 s1, s1, 44
	s_sub_i32 s1, s3, s1
	s_lshr_b32 s0, s0, 15
	v_mov_b32_e32 v0, v248
	s_and_b32 s4, s0, 0xffc0
	s_lshl_b32 s0, s1, 6
	s_and_b32 s3, s0, 0xffc0
	v_and_b32_e32 v3, 63, v0
	v_ashrrev_i32_e32 v2, 6, v0
	v_or_b32_e32 v0, s3, v3
	s_movk_i32 s0, 0xab0
	v_cmp_gt_u32_e32 vcc, s0, v0
	s_lshl_b32 s0, s3, 2
	v_readlane_b32 s1, v251, 36
	s_add_u32 s0, s1, s0
	v_readlane_b32 s1, v251, 37
	s_addc_u32 s1, s1, 0
	v_lshlrev_b32_e32 v0, 2, v3
	v_lshl_add_u64 v[4:5], s[0:1], 0, v[0:1]
	v_mov_b32_e32 v6, 0
	v_mov_b32_e32 v8, 0
	s_barrier
	v_mov_b32_e32 v218, 0
	v_mov_b32_e32 v219, 0
	v_mov_b32_e32 v220, 0
	v_mov_b32_e32 v221, 0
	v_mov_b32_e32 v222, 0
	v_mov_b32_e32 v223, 0
	v_mov_b32_e32 v224, 0
	v_mov_b32_e32 v225, 0
	v_mov_b32_e32 v226, 0
	v_mov_b32_e32 v227, 0
	v_mov_b32_e32 v228, 0
	v_mov_b32_e32 v229, 0
	v_mov_b32_e32 v230, 0
	v_mov_b32_e32 v231, 0
	v_mov_b32_e32 v232, 0
	v_mov_b32_e32 v233, 0
	s_and_saveexec_b64 s[0:1], vcc
	s_cbranch_execz .Lwin_skip_b
	v_add_u32_e32 v7, s4, v2
	s_movk_i32 s5, 0x2ac0
	v_mad_i64_i32 v[8:9], s[6:7], v7, s5, v[4:5]
	s_mov_b32 s6, 0xab00
	s_mov_b32 s7, 0
	global_load_dword v218, v[8:9], off
	v_lshl_add_u64 v[8:9], v[8:9], 0, s[6:7]
	global_load_dword v219, v[8:9], off
	v_lshl_add_u64 v[8:9], v[8:9], 0, s[6:7]
	global_load_dword v220, v[8:9], off
	v_lshl_add_u64 v[8:9], v[8:9], 0, s[6:7]
	global_load_dword v221, v[8:9], off
	v_lshl_add_u64 v[8:9], v[8:9], 0, s[6:7]
	global_load_dword v222, v[8:9], off
	v_lshl_add_u64 v[8:9], v[8:9], 0, s[6:7]
	global_load_dword v223, v[8:9], off
	v_lshl_add_u64 v[8:9], v[8:9], 0, s[6:7]
	global_load_dword v224, v[8:9], off
	v_lshl_add_u64 v[8:9], v[8:9], 0, s[6:7]
	global_load_dword v225, v[8:9], off
	v_lshl_add_u64 v[8:9], v[8:9], 0, s[6:7]
	global_load_dword v226, v[8:9], off
	v_lshl_add_u64 v[8:9], v[8:9], 0, s[6:7]
	global_load_dword v227, v[8:9], off
	v_lshl_add_u64 v[8:9], v[8:9], 0, s[6:7]
	global_load_dword v228, v[8:9], off
	v_lshl_add_u64 v[8:9], v[8:9], 0, s[6:7]
	global_load_dword v229, v[8:9], off
	v_lshl_add_u64 v[8:9], v[8:9], 0, s[6:7]
	global_load_dword v230, v[8:9], off
	v_lshl_add_u64 v[8:9], v[8:9], 0, s[6:7]
	global_load_dword v231, v[8:9], off
	v_lshl_add_u64 v[8:9], v[8:9], 0, s[6:7]
	global_load_dword v232, v[8:9], off
	v_lshl_add_u64 v[8:9], v[8:9], 0, s[6:7]
	global_load_dword v233, v[8:9], off
.Lwin_skip_b:
	s_or_b64 exec, exec, s[0:1]
	s_movk_i32 s0, 0x104
	v_mul_lo_u32 v7, v2, s0
	v_add3_u32 v9, s88, v7, v0
	s_waitcnt vmcnt(15)
	ds_write_b32 v9, v218
	s_waitcnt vmcnt(14)
	ds_write_b32 v9, v219 offset:1040
	s_waitcnt vmcnt(13)
	ds_write_b32 v9, v220 offset:2080
	s_waitcnt vmcnt(12)
	ds_write_b32 v9, v221 offset:3120
	s_waitcnt vmcnt(11)
	ds_write_b32 v9, v222 offset:4160
	s_waitcnt vmcnt(10)
	ds_write_b32 v9, v223 offset:5200
	s_waitcnt vmcnt(9)
	ds_write_b32 v9, v224 offset:6240
	s_waitcnt vmcnt(8)
	ds_write_b32 v9, v225 offset:7280
	s_waitcnt vmcnt(7)
	ds_write_b32 v9, v226 offset:8320
	s_waitcnt vmcnt(6)
	ds_write_b32 v9, v227 offset:9360
	s_waitcnt vmcnt(5)
	ds_write_b32 v9, v228 offset:10400
	s_waitcnt vmcnt(4)
	ds_write_b32 v9, v229 offset:11440
	s_waitcnt vmcnt(3)
	ds_write_b32 v9, v230 offset:12480
	s_waitcnt vmcnt(2)
	ds_write_b32 v9, v231 offset:13520
	s_waitcnt vmcnt(1)
	ds_write_b32 v9, v232 offset:14560
	s_waitcnt vmcnt(0)
	ds_write_b32 v9, v233 offset:15600
	s_lshl_b32 s1, s4, 1
	v_readlane_b32 s4, v251, 38
	s_add_u32 s4, s4, s1
	v_readlane_b32 s1, v251, 39
	s_addc_u32 s5, s1, 0
	v_lshlrev_b32_e32 v0, 1, v3
	v_lshl_add_u64 v[4:5], s[4:5], 0, v[0:1]
	v_mov_b32_e32 v0, s88
	s_movk_i32 s1, 0x104
	v_mad_u32_u24 v10, v3, s1, v0
	v_add_u32_e32 v0, 8, v2
	v_add_u32_e32 v6, 16, v2
	v_add_u32_e32 v8, 24, v2
	s_mov_b32 s0, 1
	v_mov_b32_e32 v3, v2
	s_mov_b32 s1, s3
	v_mov_b32_e32 v7, v0
	s_mov_b32 s4, 16
	v_mov_b32_e32 v9, v6
	v_mov_b32_e32 v11, v8
	s_mov_b32 s5, 0
	s_movk_i32 s10, 0x900
	s_waitcnt lgkmcnt(0)
	s_barrier
